# v56 + layer-0 ffn_down conversion moved from the phase-3 stagger to the 16 dedicated WGs of phase 7
# baseline (speedup 1.0000x reference)
; #define LAS __attribute__((address_space(3)))
; __device__ __forceinline__ void xpose_item(const float* src, int ld, bf16_t* dst, int K, int k0, LAS float* scr, int lane, const float* gk) {
;     if (src) {
; #pragma unroll 8
;         for (int i = 0; i < 32; ++i) { const int kk = 2 * i + (lane >> 5); scr[kk * 33 + (lane & 31)] = __builtin_nontemporal_load(src + (size_t)(k0 + kk) * ld + (lane & 31)); }
; __global__ void __launch_bounds__(512) mega(Args a_byval) {
;     ...
;             it = xpose_all(a.in[25] + (size_t)lyr * D * DFF, nullptr, 2048, DFF, 2048, 2048, 0, (bf16_t*)(ws + (lyr ? WS_W_D : WS_W_D0)), it, NGW, scr, lane);
.Lxpwid7_end:
	s_sub_i32 s59, s59, 0x2840
	s_cmpk_ge_i32 s59, 0x1600
	s_cbranch_scc1 .Lxpf0d7_end
	s_load_dwordx2 s[60:61], s[92:93], 0xc8
	s_load_dwordx2 s[62:63], s[92:93], 0xe8
	v_mov_b32_e32 v5, 0x2000
	v_mul_u32_u24_e32 v5, v3, v5
	v_add_u32_e32 v5, v5, v4
	v_mov_b32_e32 v10, 0x2c00
	v_mul_u32_u24_e32 v10, v8, v10
	v_lshl_add_u32 v12, v7, 4, v10
	v_add_u32_e32 v13, 0x16000, v12
	v_add_u32_e32 v14, 0x2c000, v12
	v_add_u32_e32 v15, 0x42000, v12
	s_waitcnt lgkmcnt(0)
	s_add_u32 s62, s62, 0x1f800000
	s_addc_u32 s63, s63, 0
	s_lshr_b32 s64, s59, 6
	s_and_b32 s65, s59, 63
	s_mul_i32 s66, s64, 0x80000
	s_lshl_b32 s67, s65, 7
	s_add_i32 s66, s66, s67
	s_add_u32 s66, s60, s66
	s_addc_u32 s67, s61, 0
	v_mov_b32_e32 v11, v5
	global_load_dword v20, v11, s[66:67] nt
	v_add_u32_e32 v11, 0x4000, v11
	global_load_dword v21, v11, s[66:67] nt
	v_add_u32_e32 v11, 0x4000, v11
	global_load_dword v22, v11, s[66:67] nt
	v_add_u32_e32 v11, 0x4000, v11
	global_load_dword v23, v11, s[66:67] nt
	v_add_u32_e32 v11, 0x4000, v11
	global_load_dword v24, v11, s[66:67] nt
	v_add_u32_e32 v11, 0x4000, v11
	global_load_dword v25, v11, s[66:67] nt
	v_add_u32_e32 v11, 0x4000, v11
	global_load_dword v26, v11, s[66:67] nt
	v_add_u32_e32 v11, 0x4000, v11
	global_load_dword v27, v11, s[66:67] nt
	v_add_u32_e32 v11, 0x4000, v11
	global_load_dword v28, v11, s[66:67] nt
	v_add_u32_e32 v11, 0x4000, v11
	global_load_dword v29, v11, s[66:67] nt
	v_add_u32_e32 v11, 0x4000, v11
	global_load_dword v30, v11, s[66:67] nt
	v_add_u32_e32 v11, 0x4000, v11
	global_load_dword v31, v11, s[66:67] nt
	v_add_u32_e32 v11, 0x4000, v11
	global_load_dword v32, v11, s[66:67] nt
	v_add_u32_e32 v11, 0x4000, v11
	global_load_dword v33, v11, s[66:67] nt
	v_add_u32_e32 v11, 0x4000, v11
	global_load_dword v34, v11, s[66:67] nt
	v_add_u32_e32 v11, 0x4000, v11
	global_load_dword v35, v11, s[66:67] nt
	v_add_u32_e32 v11, 0x4000, v11
	global_load_dword v36, v11, s[66:67] nt
	v_add_u32_e32 v11, 0x4000, v11
	global_load_dword v37, v11, s[66:67] nt
	v_add_u32_e32 v11, 0x4000, v11
	global_load_dword v38, v11, s[66:67] nt
	v_add_u32_e32 v11, 0x4000, v11
	global_load_dword v39, v11, s[66:67] nt
	v_add_u32_e32 v11, 0x4000, v11
	global_load_dword v40, v11, s[66:67] nt
	v_add_u32_e32 v11, 0x4000, v11
	global_load_dword v41, v11, s[66:67] nt
	v_add_u32_e32 v11, 0x4000, v11
	global_load_dword v42, v11, s[66:67] nt
	v_add_u32_e32 v11, 0x4000, v11
	global_load_dword v43, v11, s[66:67] nt
	v_add_u32_e32 v11, 0x4000, v11
	global_load_dword v44, v11, s[66:67] nt
	v_add_u32_e32 v11, 0x4000, v11
	global_load_dword v45, v11, s[66:67] nt
	v_add_u32_e32 v11, 0x4000, v11
	global_load_dword v46, v11, s[66:67] nt
	v_add_u32_e32 v11, 0x4000, v11
	global_load_dword v47, v11, s[66:67] nt
	v_add_u32_e32 v11, 0x4000, v11
	global_load_dword v48, v11, s[66:67] nt
	v_add_u32_e32 v11, 0x4000, v11
	global_load_dword v49, v11, s[66:67] nt
	v_add_u32_e32 v11, 0x4000, v11
	global_load_dword v50, v11, s[66:67] nt
	v_add_u32_e32 v11, 0x4000, v11
	global_load_dword v51, v11, s[66:67] nt

; #define LAS __attribute__((address_space(3)))
; __device__ __forceinline__ void xpose_item(const float* src, int ld, bf16_t* dst, int K, int k0, LAS float* scr, int lane, const float* gk) {
;     if (src) {
; #pragma unroll 8
;         for (int i = 0; i < 32; ++i) { const int kk = 2 * i + (lane >> 5); scr[kk * 33 + (lane & 31)] = __builtin_nontemporal_load(src + (size_t)(k0 + kk) * ld + (lane & 31)); }
;     } else {
; #pragma unroll 8
;         for (int i = 0; i < 32; ++i) { const int kk = 2 * i + (lane >> 5); scr[kk * 33 + (lane & 31)] = 0.f; }
;     }
;     const int c = lane & 7;
;     f32x4 g0 = (f32x4){1.f, 1.f, 1.f, 1.f}, g1 = g0;
;     if (gk) { g0 = *(const f32x4*)(gk + k0 + 8 * c); g1 = *(const f32x4*)(gk + k0 + 8 * c + 4); }
; __global__ void __launch_bounds__(512) mega(Args a_byval) {
;     ...
;                 it = xpose_all(a.in[22], nullptr, 2048, 4096, 2048, 2048, 0, (bf16_t*)(ws + WS_WB_OUT), it, NGW, scr, lane);
.Lxpf0d7_end:
	s_sub_i32 s59, s59, 0x1600
	s_movk_i32 s33, 0x84
.Lxcd7_done:
	s_cmp_lg_u32 s76, 7
	s_cbranch_scc1 .Lxct7_done
	v_readlane_b32 s59, v255, 5
	s_cmpk_lg_i32 s59, 0x100
	s_cbranch_scc1 .Lxct7_done
	s_cmpk_lt_i32 s94, 0xd0
	s_cbranch_scc1 .Lxct7_done
	s_cmpk_gt_i32 s94, 0xef
	s_cbranch_scc1 .Lxct7_done
	s_sub_i32 s59, s94, 0xd0
	s_lshl_b32 s59, s59, 3
	s_add_i32 s59, s59, s95
	s_mul_i32 s64, s95, 0x2100
	v_and_b32_e32 v2, 31, v200
	v_lshrrev_b32_e32 v3, 5, v200
	v_lshlrev_b32_e32 v4, 2, v2
	v_mul_u32_u24_e32 v6, 0x84, v3
	v_add3_u32 v6, v6, v4, s64
	v_and_b32_e32 v7, 7, v200
	v_lshrrev_b32_e32 v8, 3, v200
	v_mul_u32_u24_e32 v9, 0x420, v7
	v_lshl_add_u32 v9, v8, 2, v9
	v_add_u32_e32 v9, s64, v9
	s_cmpk_ge_i32 s59, 0x1000
	s_cbranch_scc1 .Lxpwot7_end
	s_load_dwordx2 s[60:61], s[92:93], 0xb0
	s_load_dwordx2 s[62:63], s[92:93], 0xe8
	v_mov_b32_e32 v5, 0x2000
	v_mul_u32_u24_e32 v5, v3, v5
	v_add_u32_e32 v5, v5, v4
	v_mov_b32_e32 v10, 0x2000
	v_mul_u32_u24_e32 v10, v8, v10
	v_lshl_add_u32 v12, v7, 4, v10
	v_add_u32_e32 v13, 0x10000, v12
	v_add_u32_e32 v14, 0x20000, v12
	v_add_u32_e32 v15, 0x30000, v12
	s_waitcnt lgkmcnt(0)
	s_add_u32 s62, s62, 0xad00000
	s_addc_u32 s63, s63, 0
	s_lshr_b32 s64, s59, 6
	s_and_b32 s65, s59, 63
	s_mul_i32 s66, s64, 0x80000
	s_lshl_b32 s67, s65, 7
	s_add_i32 s66, s66, s67
	s_add_u32 s66, s60, s66
	s_addc_u32 s67, s61, 0
	v_mov_b32_e32 v11, v5
	global_load_dword v20, v11, s[66:67] nt
	v_add_u32_e32 v11, 0x4000, v11
	global_load_dword v21, v11, s[66:67] nt
	v_add_u32_e32 v11, 0x4000, v11
	global_load_dword v22, v11, s[66:67] nt
	v_add_u32_e32 v11, 0x4000, v11
	global_load_dword v23, v11, s[66:67] nt
	v_add_u32_e32 v11, 0x4000, v11
	global_load_dword v24, v11, s[66:67] nt
	v_add_u32_e32 v11, 0x4000, v11
	global_load_dword v25, v11, s[66:67] nt
	v_add_u32_e32 v11, 0x4000, v11
	global_load_dword v26, v11, s[66:67] nt
	v_add_u32_e32 v11, 0x4000, v11
	global_load_dword v27, v11, s[66:67] nt
	v_add_u32_e32 v11, 0x4000, v11
	global_load_dword v28, v11, s[66:67] nt
	v_add_u32_e32 v11, 0x4000, v11
	global_load_dword v29, v11, s[66:67] nt
	v_add_u32_e32 v11, 0x4000, v11
	global_load_dword v30, v11, s[66:67] nt
	v_add_u32_e32 v11, 0x4000, v11
	global_load_dword v31, v11, s[66:67] nt
	v_add_u32_e32 v11, 0x4000, v11
	global_load_dword v32, v11, s[66:67] nt
	v_add_u32_e32 v11, 0x4000, v11
	global_load_dword v33, v11, s[66:67] nt
	v_add_u32_e32 v11, 0x4000, v11
	global_load_dword v34, v11, s[66:67] nt
	v_add_u32_e32 v11, 0x4000, v11
	global_load_dword v35, v11, s[66:67] nt
	v_add_u32_e32 v11, 0x4000, v11
	global_load_dword v36, v11, s[66:67] nt
	v_add_u32_e32 v11, 0x4000, v11
	global_load_dword v37, v11, s[66:67] nt
	v_add_u32_e32 v11, 0x4000, v11
	global_load_dword v38, v11, s[66:67] nt
	v_add_u32_e32 v11, 0x4000, v11
	global_load_dword v39, v11, s[66:67] nt
	v_add_u32_e32 v11, 0x4000, v11
	global_load_dword v40, v11, s[66:67] nt
	v_add_u32_e32 v11, 0x4000, v11
	global_load_dword v41, v11, s[66:67] nt
	v_add_u32_e32 v11, 0x4000, v11
	global_load_dword v42, v11, s[66:67] nt
	v_add_u32_e32 v11, 0x4000, v11
	global_load_dword v43, v11, s[66:67] nt
	v_add_u32_e32 v11, 0x4000, v11
	global_load_dword v44, v11, s[66:67] nt
	v_add_u32_e32 v11, 0x4000, v11
	global_load_dword v45, v11, s[66:67] nt
	v_add_u32_e32 v11, 0x4000, v11
	global_load_dword v46, v11, s[66:67] nt
	v_add_u32_e32 v11, 0x4000, v11
	global_load_dword v47, v11, s[66:67] nt
	v_add_u32_e32 v11, 0x4000, v11
	global_load_dword v48, v11, s[66:67] nt
	v_add_u32_e32 v11, 0x4000, v11
	global_load_dword v49, v11, s[66:67] nt
	v_add_u32_e32 v11, 0x4000, v11
	global_load_dword v50, v11, s[66:67] nt
	v_add_u32_e32 v11, 0x4000, v11
	global_load_dword v51, v11, s[66:67] nt

; __global__ void __launch_bounds__(512) mega(Args a_byval) {
;     ...
;         switch (phx) {
;         case 0: case 12: if (!PH_ON(0)) break; {
;     ...
;             it = xpose_all(a.in[27] + (size_t)lyr * D * D, nullptr, 2048, 2048, 2048, 2048, 0, (bf16_t*)(ws + (lyr ? WS_W_PG1 : WS_W_PG)), it, NGW, scr, lane, norm_ple_g + lyr * D);
.LBB0_478:
	v_readlane_b32 s0, v254, 61
	v_readlane_b32 s1, v254, 62
	s_andn2_b64 vcc, exec, s[0:1]
	s_cbranch_vccnz .LBB0_586
	s_cmp_gt_i32 s76, 1
	s_mov_b64 s[0:1], -1
	s_cbranch_scc0 .LBB0_521
	s_cmp_gt_i32 s76, 2
	s_cbranch_scc0 .LBB0_509
	s_cmp_lg_u32 s76, 3
	s_cbranch_scc1 .Lsgp3e_done
	v_readlane_b32 s59, v255, 5
	s_cmpk_lg_i32 s59, 0x100
	s_cbranch_scc1 .Lsgp3e_done
	s_cmpk_gt_i32 s94, 0x7f
	s_cbranch_scc1 .Lsgp3e_done
	s_lshl_b32 s59, s94, 3
	s_add_i32 s59, s59, s95
	s_mul_i32 s64, s95, 0x2100
	v_and_b32_e32 v2, 31, v200
	v_lshrrev_b32_e32 v3, 5, v200
	v_lshlrev_b32_e32 v4, 2, v2
	v_mul_u32_u24_e32 v6, 0x84, v3
	v_add3_u32 v6, v6, v4, s64
	v_and_b32_e32 v7, 7, v200
	v_lshrrev_b32_e32 v8, 3, v200
	v_mul_u32_u24_e32 v9, 0x420, v7
	v_lshl_add_u32 v9, v8, 2, v9
	v_add_u32_e32 v9, s64, v9
	s_cmpk_ge_i32 s59, 0x800
	s_cbranch_scc1 .Lxpq0p3e_end
	s_load_dwordx2 s[60:61], s[92:93], 0xd8
	s_load_dwordx2 s[62:63], s[92:93], 0xe8
	s_load_dwordx2 s[64:65], s[92:93], 0x20
	v_mov_b32_e32 v5, 0x2000
	v_mul_u32_u24_e32 v5, v3, v5
	v_add_u32_e32 v5, v5, v4
	v_mov_b32_e32 v10, 0x1000
	v_mul_u32_u24_e32 v10, v8, v10
	v_lshl_add_u32 v12, v7, 4, v10
	v_add_u32_e32 v13, 0x8000, v12
	v_add_u32_e32 v14, 0x10000, v12
	v_add_u32_e32 v15, 0x18000, v12
	s_waitcnt lgkmcnt(0)
	s_add_u32 s62, s62, 0x7b00000
	s_addc_u32 s63, s63, 0
	s_add_u32 s64, s64, 0x0
	s_addc_u32 s65, s65, 0
	v_lshlrev_b32_e32 v16, 5, v7
	v_mov_b32_e32 v17, v0
	v_lshl_add_u64 v[16:17], s[64:65], 0, v[16:17]
	s_lshr_b32 s64, s59, 6
	s_and_b32 s65, s59, 63
	s_mul_i32 s66, s64, 0x80000
	s_lshl_b32 s67, s65, 7
	s_add_i32 s66, s66, s67
	s_add_u32 s66, s60, s66
	s_addc_u32 s67, s61, 0
	s_lshl_b32 s64, s64, 8
	s_mov_b32 s65, 0
	v_lshl_add_u64 v[18:19], s[64:65], 0, v[16:17]
	global_load_dwordx4 v[52:55], v[18:19], off
	global_load_dwordx4 v[56:59], v[18:19], off offset:16
	v_mov_b32_e32 v11, v5
	global_load_dword v20, v11, s[66:67] nt
	v_add_u32_e32 v11, 0x4000, v11
	global_load_dword v21, v11, s[66:67] nt
	v_add_u32_e32 v11, 0x4000, v11
	global_load_dword v22, v11, s[66:67] nt
	v_add_u32_e32 v11, 0x4000, v11
	global_load_dword v23, v11, s[66:67] nt
	v_add_u32_e32 v11, 0x4000, v11
	global_load_dword v24, v11, s[66:67] nt
	v_add_u32_e32 v11, 0x4000, v11
	global_load_dword v25, v11, s[66:67] nt
	v_add_u32_e32 v11, 0x4000, v11
	global_load_dword v26, v11, s[66:67] nt
	v_add_u32_e32 v11, 0x4000, v11
	global_load_dword v27, v11, s[66:67] nt
	v_add_u32_e32 v11, 0x4000, v11
	global_load_dword v28, v11, s[66:67] nt
	v_add_u32_e32 v11, 0x4000, v11
	global_load_dword v29, v11, s[66:67] nt
	v_add_u32_e32 v11, 0x4000, v11
	global_load_dword v30, v11, s[66:67] nt
	v_add_u32_e32 v11, 0x4000, v11
	global_load_dword v31, v11, s[66:67] nt
	v_add_u32_e32 v11, 0x4000, v11
	global_load_dword v32, v11, s[66:67] nt
	v_add_u32_e32 v11, 0x4000, v11
	global_load_dword v33, v11, s[66:67] nt
	v_add_u32_e32 v11, 0x4000, v11
	global_load_dword v34, v11, s[66:67] nt
	v_add_u32_e32 v11, 0x4000, v11
	global_load_dword v35, v11, s[66:67] nt
	v_add_u32_e32 v11, 0x4000, v11
	global_load_dword v36, v11, s[66:67] nt
	v_add_u32_e32 v11, 0x4000, v11
	global_load_dword v37, v11, s[66:67] nt
	v_add_u32_e32 v11, 0x4000, v11
	global_load_dword v38, v11, s[66:67] nt
	v_add_u32_e32 v11, 0x4000, v11
	global_load_dword v39, v11, s[66:67] nt
	v_add_u32_e32 v11, 0x4000, v11
	global_load_dword v40, v11, s[66:67] nt
	v_add_u32_e32 v11, 0x4000, v11
	global_load_dword v41, v11, s[66:67] nt
	v_add_u32_e32 v11, 0x4000, v11
	global_load_dword v42, v11, s[66:67] nt
	v_add_u32_e32 v11, 0x4000, v11
	global_load_dword v43, v11, s[66:67] nt
	v_add_u32_e32 v11, 0x4000, v11
	global_load_dword v44, v11, s[66:67] nt
	v_add_u32_e32 v11, 0x4000, v11
	global_load_dword v45, v11, s[66:67] nt
	v_add_u32_e32 v11, 0x4000, v11
	global_load_dword v46, v11, s[66:67] nt
	v_add_u32_e32 v11, 0x4000, v11
	global_load_dword v47, v11, s[66:67] nt
	v_add_u32_e32 v11, 0x4000, v11
	global_load_dword v48, v11, s[66:67] nt
	v_add_u32_e32 v11, 0x4000, v11
	global_load_dword v49, v11, s[66:67] nt
	v_add_u32_e32 v11, 0x4000, v11
	global_load_dword v50, v11, s[66:67] nt
	v_add_u32_e32 v11, 0x4000, v11
	global_load_dword v51, v11, s[66:67] nt

; #define LAS __attribute__((address_space(3)))
; __device__ __forceinline__ void xpose_item(const float* src, int ld, bf16_t* dst, int K, int k0, LAS float* scr, int lane, const float* gk) {
;     if (src) {
; #pragma unroll 8
;         for (int i = 0; i < 32; ++i) { const int kk = 2 * i + (lane >> 5); scr[kk * 33 + (lane & 31)] = __builtin_nontemporal_load(src + (size_t)(k0 + kk) * ld + (lane & 31)); }
;     } else {
; #pragma unroll 8
;         for (int i = 0; i < 32; ++i) { const int kk = 2 * i + (lane >> 5); scr[kk * 33 + (lane & 31)] = 0.f; }
;     }
;     const int c = lane & 7;
;     f32x4 g0 = (f32x4){1.f, 1.f, 1.f, 1.f}, g1 = g0;
;     if (gk) { g0 = *(const f32x4*)(gk + k0 + 8 * c); g1 = *(const f32x4*)(gk + k0 + 8 * c + 4); }
; __global__ void __launch_bounds__(512) mega(Args a_byval) {
;     ...
;             it = xpose_all(a.in[27] + (size_t)lyr * D * D, nullptr, 2048, 2048, 2048, 2048, 0, (bf16_t*)(ws + (lyr ? WS_W_PG1 : WS_W_PG)), it, NGW, scr, lane, norm_ple_g + lyr * D);
.LBB0_507:
	s_waitcnt vmcnt(0)
	s_barrier
	s_cmp_lg_u32 s76, 3
	s_cbranch_scc1 .Lsgp3x_done
	v_readlane_b32 s59, v255, 5
	s_cmpk_lg_i32 s59, 0x100
	s_cbranch_scc1 .Lsgp3x_done
	s_cmpk_lt_i32 s94, 0x80
	s_cbranch_scc1 .Lsgp3x_done
	s_lshl_b32 s59, s94, 3
	s_add_i32 s59, s59, s95
	s_mul_i32 s64, s95, 0x2100
	v_and_b32_e32 v2, 31, v200
	v_lshrrev_b32_e32 v3, 5, v200
	v_lshlrev_b32_e32 v4, 2, v2
	v_mul_u32_u24_e32 v6, 0x84, v3
	v_add3_u32 v6, v6, v4, s64
	v_and_b32_e32 v7, 7, v200
	v_lshrrev_b32_e32 v8, 3, v200
	v_mul_u32_u24_e32 v9, 0x420, v7
	v_lshl_add_u32 v9, v8, 2, v9
	v_add_u32_e32 v9, s64, v9
	s_cmpk_ge_i32 s59, 0x800
	s_cbranch_scc1 .Lxpq0p3x_end
	s_load_dwordx2 s[60:61], s[92:93], 0xd8
	s_load_dwordx2 s[62:63], s[92:93], 0xe8
	s_load_dwordx2 s[64:65], s[92:93], 0x20
	v_mov_b32_e32 v5, 0x2000
	v_mul_u32_u24_e32 v5, v3, v5
	v_add_u32_e32 v5, v5, v4
	v_mov_b32_e32 v10, 0x1000
	v_mul_u32_u24_e32 v10, v8, v10
	v_lshl_add_u32 v12, v7, 4, v10
	v_add_u32_e32 v13, 0x8000, v12
	v_add_u32_e32 v14, 0x10000, v12
	v_add_u32_e32 v15, 0x18000, v12
	s_waitcnt lgkmcnt(0)
	s_add_u32 s62, s62, 0x7b00000
	s_addc_u32 s63, s63, 0
	s_add_u32 s64, s64, 0x0
	s_addc_u32 s65, s65, 0
	v_lshlrev_b32_e32 v16, 5, v7
	v_mov_b32_e32 v17, v0
	v_lshl_add_u64 v[16:17], s[64:65], 0, v[16:17]
	s_lshr_b32 s64, s59, 6
	s_and_b32 s65, s59, 63
	s_mul_i32 s66, s64, 0x80000
	s_lshl_b32 s67, s65, 7
	s_add_i32 s66, s66, s67
	s_add_u32 s66, s60, s66
	s_addc_u32 s67, s61, 0
	s_lshl_b32 s64, s64, 8
	s_mov_b32 s65, 0
	v_lshl_add_u64 v[18:19], s[64:65], 0, v[16:17]
	global_load_dwordx4 v[52:55], v[18:19], off
	global_load_dwordx4 v[56:59], v[18:19], off offset:16
	v_mov_b32_e32 v11, v5
	global_load_dword v20, v11, s[66:67] nt
	v_add_u32_e32 v11, 0x4000, v11
	global_load_dword v21, v11, s[66:67] nt
	v_add_u32_e32 v11, 0x4000, v11
	global_load_dword v22, v11, s[66:67] nt
	v_add_u32_e32 v11, 0x4000, v11
	global_load_dword v23, v11, s[66:67] nt
	v_add_u32_e32 v11, 0x4000, v11
	global_load_dword v24, v11, s[66:67] nt
	v_add_u32_e32 v11, 0x4000, v11
	global_load_dword v25, v11, s[66:67] nt
	v_add_u32_e32 v11, 0x4000, v11
	global_load_dword v26, v11, s[66:67] nt
	v_add_u32_e32 v11, 0x4000, v11
	global_load_dword v27, v11, s[66:67] nt
	v_add_u32_e32 v11, 0x4000, v11
	global_load_dword v28, v11, s[66:67] nt
	v_add_u32_e32 v11, 0x4000, v11
	global_load_dword v29, v11, s[66:67] nt
	v_add_u32_e32 v11, 0x4000, v11
	global_load_dword v30, v11, s[66:67] nt
	v_add_u32_e32 v11, 0x4000, v11
	global_load_dword v31, v11, s[66:67] nt
	v_add_u32_e32 v11, 0x4000, v11
	global_load_dword v32, v11, s[66:67] nt
	v_add_u32_e32 v11, 0x4000, v11
	global_load_dword v33, v11, s[66:67] nt
	v_add_u32_e32 v11, 0x4000, v11
	global_load_dword v34, v11, s[66:67] nt
	v_add_u32_e32 v11, 0x4000, v11
	global_load_dword v35, v11, s[66:67] nt
	v_add_u32_e32 v11, 0x4000, v11
	global_load_dword v36, v11, s[66:67] nt
	v_add_u32_e32 v11, 0x4000, v11
	global_load_dword v37, v11, s[66:67] nt
	v_add_u32_e32 v11, 0x4000, v11
	global_load_dword v38, v11, s[66:67] nt
	v_add_u32_e32 v11, 0x4000, v11
	global_load_dword v39, v11, s[66:67] nt
	v_add_u32_e32 v11, 0x4000, v11
	global_load_dword v40, v11, s[66:67] nt
	v_add_u32_e32 v11, 0x4000, v11
	global_load_dword v41, v11, s[66:67] nt
	v_add_u32_e32 v11, 0x4000, v11
	global_load_dword v42, v11, s[66:67] nt
	v_add_u32_e32 v11, 0x4000, v11
	global_load_dword v43, v11, s[66:67] nt
	v_add_u32_e32 v11, 0x4000, v11
	global_load_dword v44, v11, s[66:67] nt
	v_add_u32_e32 v11, 0x4000, v11
	global_load_dword v45, v11, s[66:67] nt
	v_add_u32_e32 v11, 0x4000, v11
	global_load_dword v46, v11, s[66:67] nt
	v_add_u32_e32 v11, 0x4000, v11
	global_load_dword v47, v11, s[66:67] nt
	v_add_u32_e32 v11, 0x4000, v11
	global_load_dword v48, v11, s[66:67] nt
	v_add_u32_e32 v11, 0x4000, v11
	global_load_dword v49, v11, s[66:67] nt
	v_add_u32_e32 v11, 0x4000, v11
	global_load_dword v50, v11, s[66:67] nt
	v_add_u32_e32 v11, 0x4000, v11
	global_load_dword v51, v11, s[66:67] nt
